# queue pre-claim of the next index except while a scan or select unit runs; attention row-max canonicalising self-max removed
# baseline (speedup 1.0000x reference)
.Lqp0_have:
	v_mov_b32_e32 v3, s0
	v_mov_b32_e32 v255, -1
	s_sub_u32 s8, s0, 0x100
	s_cmp_lt_u32 s8, 64
	s_cbranch_scc1 .LBB0_690
	s_sub_u32 s8, s0, 576
	s_cmp_ge_u32 s8, 0x300
	s_cbranch_scc1 .Lqp0_pf
	s_mul_hi_u32 s9, s8, 0xaaaaaaab
	s_lshr_b32 s9, s9, 1
	s_mul_i32 s9, s9, 3
	s_cmp_eq_u32 s8, s9
	s_cbranch_scc1 .LBB0_690
.Lqp0_pf:
	v_mov_b32_e32 v255, 1
	s_nop 0
	global_atomic_add v255, v206, v255, s[90:91] sc0

.Lqp1_pf:
	v_mov_b32_e32 v255, 1
	s_nop 0
	global_atomic_add v255, v206, v255, s[90:91] offset:256 sc0
